# FFN-in epilogue: removed dead zero-initialisations before full-row DPP moves (hazard distances re-checked)
# baseline (speedup 1.0000x reference)
.Lepi0_ffnin:
	v_lshl_add_u32 v164, s84, 8, v231
	v_lshl_add_u64 v[44:45], v[164:165], 2, s[34:35]
	global_load_dword v184, v[44:45], off
	v_or_b32_e32 v182, 16, v164
	v_mov_b32_e32 v183, v165
	v_lshl_add_u64 v[44:45], v[182:183], 2, s[34:35]
	global_load_dword v186, v[44:45], off
	v_or_b32_e32 v44, 32, v164
	v_mov_b32_e32 v45, v165
	v_lshl_add_u64 v[44:45], v[44:45], 2, s[34:35]
	v_or_b32_e32 v180, 48, v164
	v_mov_b32_e32 v181, v165
	global_load_dword v200, v[44:45], off
	v_lshl_add_u64 v[44:45], v[180:181], 2, s[34:35]
	v_add_u32_e32 v178, 0x80, v164
	v_mov_b32_e32 v179, v165
	global_load_dword v185, v[44:45], off
	v_lshl_add_u64 v[44:45], v[178:179], 2, s[34:35]
	v_add_u32_e32 v174, 0x90, v164
	v_mov_b32_e32 v175, v165
	global_load_dword v183, v[44:45], off
	v_lshl_add_u64 v[44:45], v[174:175], 2, s[34:35]
	global_load_dword v181, v[44:45], off
	v_add_u32_e32 v44, 0xa0, v164
	v_mov_b32_e32 v45, v165
	v_lshl_add_u64 v[44:45], v[44:45], 2, s[34:35]
	global_load_dword v175, v[44:45], off
	v_add_u32_e32 v44, 0xb0, v164
	v_mov_b32_e32 v45, v165
	v_lshl_or_b32 v176, s88, 7, v235
	v_lshl_add_u64 v[44:45], v[44:45], 2, s[34:35]
	v_ashrrev_i32_e32 v177, 31, v176
	v_readlane_b32 s44, v254, 1
	global_load_dword v179, v[44:45], off
	v_lshlrev_b64 v[44:45], 2, v[176:177]
	v_readlane_b32 s48, v254, 5
	v_readlane_b32 s49, v254, 6
	v_readlane_b32 s50, v254, 7
	v_readlane_b32 s51, v254, 8
	v_lshl_add_u64 v[48:49], s[48:49], 0, v[44:45]
	v_lshl_add_u64 v[52:53], s[96:97], 0, v[44:45]
	v_lshl_add_u64 v[56:57], s[86:87], 0, v[44:45]
	v_lshl_add_u64 v[80:81], s[50:51], 0, v[44:45]
	global_load_dwordx4 v[44:47], v[48:49], off offset:16
	global_load_dwordx4 v[68:71], v[48:49], off
	s_nop 0
	global_load_dwordx4 v[48:51], v[52:53], off offset:16
	global_load_dwordx4 v[72:75], v[52:53], off
	s_nop 0
	global_load_dwordx4 v[52:55], v[56:57], off offset:16
	global_load_dwordx4 v[76:79], v[56:57], off
	s_nop 0
	global_load_dwordx4 v[56:59], v[80:81], off offset:16
	s_nop 0
	global_load_dwordx4 v[80:83], v[80:81], off
	v_mov_b32_e32 v191, 0
	v_mov_b32_e32 v193, 0
	v_mov_b32_e32 v196, 0
	s_lshl_b32 s3, s84, 2
	v_mov_b32_e32 v198, 0
	s_add_i32 s3, s3, s10
	v_mov_b32_e32 v197, 0
	s_mul_i32 s51, s3, 6
	v_mov_b32_e32 v199, 0
	v_readlane_b32 s45, v254, 2
	v_readlane_b32 s46, v254, 3
	v_readlane_b32 s47, v254, 4
	s_waitcnt vmcnt(0)
	v_fmamk_f32 v177, v184, 0x3a800000, v239
	v_cmp_gt_f32_e32 vcc, s33, v177
	v_mul_f32_e32 v184, 0x4b800000, v177
	s_nop 0
	v_cndmask_b32_e32 v177, v177, v184, vcc
	v_rsq_f32_e32 v177, v177
	s_nop 0
	v_mul_f32_e32 v184, 0x45800000, v177
	v_cndmask_b32_e32 v188, v177, v184, vcc
	v_fmamk_f32 v177, v186, 0x3a800000, v239
	v_cmp_gt_f32_e32 vcc, s33, v177
	v_mul_f32_e32 v184, 0x4b800000, v177
	v_pk_mul_f32 v[186:187], v[156:157], v[188:189] op_sel_hi:[1,0]
	v_cndmask_b32_e32 v177, v177, v184, vcc
	v_rsq_f32_e32 v177, v177
	v_cndmask_b32_e64 v156, v186, 0, s[38:39]
	v_pk_mul_f32 v[194:195], v[158:159], v[188:189] op_sel_hi:[1,0]
	v_mul_f32_e32 v184, 0x45800000, v177
	v_cndmask_b32_e32 v184, v177, v184, vcc
	v_mov_b32_dpp v190, v156 row_ror:1 row_mask:0xf bank_mask:0xf
	v_pk_mul_f32 v[156:157], v[152:153], v[184:185] op_sel_hi:[1,0]
	v_pk_mul_f32 v[158:159], v[154:155], v[184:185] op_sel_hi:[1,0]
	v_cndmask_b32_e64 v152, v186, v156, s[42:43]
	v_add_u32_e32 v155, s51, v234
	s_nop 0
	v_mov_b32_dpp v192, v152 row_ror:15 row_mask:0xf bank_mask:0xf
	v_cndmask_b32_e64 v152, v187, 0, s[38:39]
	s_nop 1
	v_mov_b32_dpp v191, v152 row_ror:1 row_mask:0xf bank_mask:0xf
	v_cndmask_b32_e64 v152, v187, v157, s[42:43]
	s_nop 1
	v_mov_b32_dpp v193, v152 row_ror:15 row_mask:0xf bank_mask:0xf
	v_cndmask_b32_e64 v152, v194, 0, s[38:39]
	s_nop 1
	v_mov_b32_dpp v196, v152 row_ror:1 row_mask:0xf bank_mask:0xf
	v_cndmask_b32_e64 v152, v194, v158, s[42:43]
	s_nop 1
	v_mov_b32_dpp v198, v152 row_ror:15 row_mask:0xf bank_mask:0xf
	v_cndmask_b32_e64 v152, v195, 0, s[38:39]
	s_nop 1
	v_mov_b32_dpp v197, v152 row_ror:1 row_mask:0xf bank_mask:0xf
	v_cndmask_b32_e64 v152, v195, v159, s[42:43]
	s_nop 1
	v_mov_b32_dpp v199, v152 row_ror:15 row_mask:0xf bank_mask:0xf
	s_and_saveexec_b64 s[0:1], s[70:71]
	s_cbranch_execz .LBB0_706
	v_mad_u64_u32 v[202:203], s[22:23], v155, s65, v[176:177]
	v_mov_b32_e32 v203, v165
	v_cvt_pk_bf16_f32 v152, v186, v187
	v_cvt_pk_bf16_f32 v153, v194, v195
	v_lshl_add_u64 v[202:203], v[202:203], 1, s[30:31]
	global_store_dwordx2 v[202:203], v[152:153], off

.LBB0_708:
	s_or_b64 exec, exec, s[0:1]
	v_fmamk_f32 v148, v200, 0x3a800000, v239
	v_cmp_gt_f32_e32 vcc, s33, v148
	v_mul_f32_e32 v149, 0x4b800000, v148
	v_mov_b32_e32 v216, 0
	v_cndmask_b32_e32 v148, v148, v149, vcc
	v_rsq_f32_e32 v148, v148
	v_mov_b32_e32 v218, 0
	v_mul_f32_e32 v149, 0x45800000, v148
	v_cndmask_b32_e32 v154, v148, v149, vcc
	v_fmamk_f32 v148, v185, 0x3a800000, v239
	v_cmp_gt_f32_e32 vcc, s33, v148
	v_mul_f32_e32 v149, 0x4b800000, v148
	v_pk_mul_f32 v[200:201], v[140:141], v[154:155] op_sel_hi:[1,0]
	v_cndmask_b32_e32 v148, v148, v149, vcc
	v_rsq_f32_e32 v148, v148
	v_cndmask_b32_e64 v140, v156, v200, s[42:43]
	v_mul_f32_e32 v149, 0x45800000, v148
	v_cndmask_b32_e32 v150, v148, v149, vcc
	v_cndmask_b32_e64 v148, v156, v186, s[38:39]
	v_mov_b32_dpp v218, v140 row_ror:15 row_mask:0xf bank_mask:0xf
	v_cndmask_b32_e64 v140, v157, v201, s[42:43]
	v_mov_b32_dpp v216, v148 row_ror:1 row_mask:0xf bank_mask:0xf
	v_cndmask_b32_e64 v148, v157, v187, s[38:39]
	v_mov_b32_dpp v219, v140 row_ror:15 row_mask:0xf bank_mask:0xf
	v_cndmask_b32_e64 v140, v200, v156, s[38:39]
	v_mov_b32_dpp v217, v148 row_ror:1 row_mask:0xf bank_mask:0xf
	v_cndmask_b32_e64 v148, v158, v194, s[38:39]
	v_mov_b32_e32 v206, 0
	v_mov_b32_e32 v208, 0
	v_mov_b32_dpp v204, v148 row_ror:1 row_mask:0xf bank_mask:0xf
	v_cndmask_b32_e64 v148, v159, v195, s[38:39]
	v_mov_b32_dpp v206, v140 row_ror:1 row_mask:0xf bank_mask:0xf
	v_mov_b32_e32 v207, 0
	v_mov_b32_dpp v205, v148 row_ror:1 row_mask:0xf bank_mask:0xf
	v_pk_mul_f32 v[148:149], v[144:145], v[150:151] op_sel_hi:[1,0]
	v_cndmask_b32_e64 v140, v200, v148, s[42:43]
	v_pk_mul_f32 v[202:203], v[142:143], v[154:155] op_sel_hi:[1,0]
	v_mov_b32_e32 v214, 0
	v_mov_b32_dpp v208, v140 row_ror:15 row_mask:0xf bank_mask:0xf
	v_cndmask_b32_e64 v140, v201, v157, s[38:39]
	v_mov_b32_e32 v215, 0
	v_pk_mul_f32 v[144:145], v[146:147], v[150:151] op_sel_hi:[1,0]
	v_mov_b32_dpp v207, v140 row_ror:1 row_mask:0xf bank_mask:0xf
	v_cndmask_b32_e64 v140, v201, v149, s[42:43]
	v_mov_b32_e32 v210, 0
	v_mov_b32_e32 v212, 0
	v_mov_b32_dpp v209, v140 row_ror:15 row_mask:0xf bank_mask:0xf
	v_cndmask_b32_e64 v140, v158, v202, s[42:43]
	v_mov_b32_e32 v211, 0
	v_mov_b32_e32 v213, 0
	v_mov_b32_dpp v214, v140 row_ror:15 row_mask:0xf bank_mask:0xf
	v_cndmask_b32_e64 v140, v159, v203, s[42:43]
	v_cndmask_b32_e64 v141, v148, v200, s[38:39]
	v_mov_b32_e32 v142, 0
	v_mov_b32_dpp v215, v140 row_ror:15 row_mask:0xf bank_mask:0xf
	v_cndmask_b32_e64 v140, v202, v158, s[38:39]
	v_cndmask_b32_e64 v143, v149, v201, s[38:39]
	v_cndmask_b32_e64 v146, v149, 0, s[42:43]
	v_mov_b32_dpp v210, v140 row_ror:1 row_mask:0xf bank_mask:0xf
	v_cndmask_b32_e64 v140, v202, v144, s[42:43]
	v_cndmask_b32_e64 v147, v144, v202, s[38:39]
	v_mov_b32_e32 v152, 0
	v_mov_b32_dpp v212, v140 row_ror:15 row_mask:0xf bank_mask:0xf
	v_cndmask_b32_e64 v140, v203, v159, s[38:39]
	v_cndmask_b32_e64 v151, v145, v203, s[38:39]
	v_mov_b32_e32 v153, 0
	v_mov_b32_dpp v211, v140 row_ror:1 row_mask:0xf bank_mask:0xf
	v_cndmask_b32_e64 v140, v203, v145, s[42:43]
	v_add_u32_e32 v240, s51, v233
	s_nop 0
	v_mov_b32_dpp v213, v140 row_ror:15 row_mask:0xf bank_mask:0xf
	s_nop 1
	v_mov_b32_dpp v140, v141 row_ror:1 row_mask:0xf bank_mask:0xf
	v_cndmask_b32_e64 v141, v148, 0, s[42:43]
	s_nop 1
	v_mov_b32_dpp v142, v141 row_ror:15 row_mask:0xf bank_mask:0xf
	s_nop 1
	v_mov_b32_dpp v141, v143 row_ror:1 row_mask:0xf bank_mask:0xf
	s_nop 1
	v_mov_b32_dpp v143, v146 row_ror:15 row_mask:0xf bank_mask:0xf
	s_nop 1
	v_mov_b32_dpp v146, v147 row_ror:1 row_mask:0xf bank_mask:0xf
	v_cndmask_b32_e64 v147, v144, 0, s[42:43]
	s_nop 1
	v_mov_b32_dpp v152, v147 row_ror:15 row_mask:0xf bank_mask:0xf
	s_nop 1
	v_mov_b32_dpp v147, v151 row_ror:1 row_mask:0xf bank_mask:0xf
	v_cndmask_b32_e64 v151, v145, 0, s[42:43]
	s_nop 1
	v_mov_b32_dpp v153, v151 row_ror:15 row_mask:0xf bank_mask:0xf
	s_and_saveexec_b64 s[0:1], s[74:75]
	s_cbranch_execz .LBB0_710
	v_mad_u64_u32 v[226:227], s[22:23], v240, s65, v[176:177]
	v_mov_b32_e32 v227, v165
	v_cvt_pk_bf16_f32 v224, v148, v149
	v_cvt_pk_bf16_f32 v225, v144, v145
	v_lshl_add_u64 v[226:227], v[226:227], 1, s[30:31]
	global_store_dwordx2 v[226:227], v[224:225], off

.LBB0_712:
	s_or_b64 exec, exec, s[0:1]
	v_mov_b32_e32 v185, v184
	v_pk_mul_f32 v[132:133], v[132:133], v[188:189]
	v_pk_mul_f32 v[128:129], v[128:129], v[184:185]
	v_cndmask_b32_e64 v224, v132, 0, s[38:39]
	v_mov_b32_e32 v226, 0
	v_mov_b32_e32 v227, 0
	v_cndmask_b32_e64 v228, v133, v129, s[42:43]
	v_mov_b32_dpp v226, v224 row_ror:1 row_mask:0xf bank_mask:0xf
	v_pk_mul_f32 v[224:225], v[124:125], v[188:189]
	v_cndmask_b32_e64 v125, v132, v128, s[42:43]
	v_pk_mul_f32 v[130:131], v[130:131], v[184:185]
	v_pk_mul_f32 v[134:135], v[134:135], v[188:189]
	v_mov_b32_dpp v124, v125 row_ror:15 row_mask:0xf bank_mask:0xf
	v_cndmask_b32_e64 v125, v133, 0, s[38:39]
	v_cndmask_b32_e64 v229, v134, 0, s[38:39]
	v_pk_mul_f32 v[126:127], v[126:127], v[188:189]
	v_mov_b32_dpp v227, v125 row_ror:1 row_mask:0xf bank_mask:0xf
	v_cndmask_b32_e64 v189, v134, v130, s[42:43]
	v_mov_b32_dpp v125, v228 row_ror:15 row_mask:0xf bank_mask:0xf
	v_mov_b32_e32 v228, 0
	v_mov_b32_dpp v188, v189 row_ror:15 row_mask:0xf bank_mask:0xf
	v_cndmask_b32_e64 v189, v135, 0, s[38:39]
	v_mov_b32_dpp v228, v229 row_ror:1 row_mask:0xf bank_mask:0xf
	v_cndmask_b32_e64 v241, v135, v131, s[42:43]
	s_nop 0
	v_mov_b32_dpp v229, v189 row_ror:1 row_mask:0xf bank_mask:0xf
	s_nop 1
	v_mov_b32_dpp v189, v241 row_ror:15 row_mask:0xf bank_mask:0xf
	s_and_saveexec_b64 s[0:1], s[40:41]
	s_cbranch_execnz .LBB0_735
	s_or_b64 exec, exec, s[0:1]
	v_or_b32_e32 v124, 4, v176
	s_and_saveexec_b64 s[0:1], s[70:71]
	s_cbranch_execnz .LBB0_736

.LBB0_716:
	s_or_b64 exec, exec, s[0:1]
	v_pk_fma_f32 v[126:127], v[68:69], v[216:217], v[80:81]
	v_pk_mul_f32 v[122:123], v[122:123], v[184:185]
	v_pk_fma_f32 v[126:127], v[156:157], v[72:73], v[126:127]
	v_pk_mul_f32 v[156:157], v[120:121], v[184:185]
	v_pk_fma_f32 v[126:127], v[76:77], v[218:219], v[126:127]
	v_pk_fma_f32 v[190:191], v[70:71], v[210:211], v[82:83]
	v_and_b32_e32 v121, 0x7fffffff, v127
	v_and_b32_e32 v120, 0x7fffffff, v126
	v_pk_fma_f32 v[120:121], v[120:121], s[56:57], 1.0 op_sel_hi:[1,0,0]
	v_pk_fma_f32 v[190:191], v[74:75], v[202:203], v[190:191]
	v_rcp_f32_e32 v186, v120
	v_rcp_f32_e32 v187, v121
	v_pk_fma_f32 v[120:121], v[70:71], v[204:205], v[82:83]
	v_pk_fma_f32 v[190:191], v[78:79], v[212:213], v[190:191]
	v_pk_fma_f32 v[158:159], v[158:159], v[74:75], v[120:121]
	v_mov_b64_e32 v[120:121], s[64:65]
	v_pk_fma_f32 v[158:159], v[78:79], v[214:215], v[158:159]
	v_pk_fma_f32 v[188:189], v[186:187], s[58:59], v[120:121] op_sel_hi:[1,0,0]
	v_and_b32_e32 v195, 0x7fffffff, v159
	v_and_b32_e32 v194, 0x7fffffff, v158
	v_pk_fma_f32 v[194:195], v[194:195], s[56:57], 1.0 op_sel_hi:[1,0,0]
	v_pk_mul_f32 v[192:193], v[158:159], v[158:159]
	v_rcp_f32_e32 v194, v194
	v_rcp_f32_e32 v195, v195
	v_pk_mul_f32 v[192:193], v[192:193], s[54:55] op_sel_hi:[1,0]
	v_pk_fma_f32 v[188:189], v[186:187], v[188:189], s[66:67] op_sel_hi:[1,1,0]
	v_exp_f32_e32 v192, v192
	v_pk_fma_f32 v[196:197], v[194:195], s[58:59], v[120:121] op_sel_hi:[1,0,0]
	v_exp_f32_e32 v193, v193
	v_pk_fma_f32 v[196:197], v[194:195], v[196:197], s[66:67] op_sel_hi:[1,1,0]
	v_pk_fma_f32 v[188:189], v[186:187], v[188:189], s[68:69] op_sel_hi:[1,1,0]
	v_pk_fma_f32 v[196:197], v[194:195], v[196:197], s[68:69] op_sel_hi:[1,1,0]
	v_cmp_gt_f32_e32 vcc, 0, v159
	v_pk_fma_f32 v[196:197], v[194:195], v[196:197], s[72:73] op_sel_hi:[1,1,0]
	v_pk_fma_f32 v[188:189], v[186:187], v[188:189], s[72:73] op_sel_hi:[1,1,0]
	v_pk_mul_f32 v[194:195], v[194:195], v[196:197]
	v_pk_mul_f32 v[196:197], v[126:127], v[126:127]
	v_pk_mul_f32 v[192:193], v[192:193], v[194:195]
	v_pk_mul_f32 v[196:197], v[196:197], s[54:55] op_sel_hi:[1,0]
	v_pk_mul_f32 v[194:195], v[158:159], v[192:193]
	v_exp_f32_e32 v196, v196
	v_exp_f32_e32 v197, v197
	v_pk_fma_f32 v[192:193], v[158:159], v[192:193], v[158:159] neg_lo:[1,0,0] neg_hi:[1,0,0]
	v_pk_mul_f32 v[186:187], v[186:187], v[188:189]
	v_cndmask_b32_e32 v159, v193, v195, vcc
	v_cmp_gt_f32_e32 vcc, 0, v158
	v_pk_fma_f32 v[188:189], v[68:69], v[206:207], v[80:81]
	v_mov_b32_e32 v155, v154
	v_cndmask_b32_e32 v158, v192, v194, vcc
	v_pk_mul_f32 v[122:123], v[122:123], v[158:159]
	v_pk_mul_f32 v[158:159], v[196:197], v[186:187]
	v_cmp_gt_f32_e32 vcc, 0, v127
	v_pk_mul_f32 v[186:187], v[126:127], v[158:159]
	v_pk_fma_f32 v[158:159], v[126:127], v[158:159], v[126:127] neg_lo:[1,0,0] neg_hi:[1,0,0]
	v_pk_fma_f32 v[188:189], v[72:73], v[200:201], v[188:189]
	v_cndmask_b32_e32 v127, v159, v187, vcc
	v_cmp_gt_f32_e32 vcc, 0, v126
	v_pk_fma_f32 v[188:189], v[76:77], v[208:209], v[188:189]
	v_pk_mul_f32 v[118:119], v[118:119], v[154:155]
	v_cndmask_b32_e32 v126, v158, v186, vcc
	v_pk_mul_f32 v[156:157], v[156:157], v[126:127]
	v_cvt_pk_bf16_f32 v127, v122, v123
	v_cvt_pk_bf16_f32 v126, v156, v157
	v_and_b32_e32 v157, 0x7fffffff, v191
	v_and_b32_e32 v156, 0x7fffffff, v190
	v_pk_fma_f32 v[156:157], v[156:157], s[56:57], 1.0 op_sel_hi:[1,0,0]
	v_pk_mul_f32 v[122:123], v[190:191], v[190:191]
	v_rcp_f32_e32 v156, v156
	v_rcp_f32_e32 v157, v157
	v_pk_mul_f32 v[122:123], v[122:123], s[54:55] op_sel_hi:[1,0]
	v_cmp_gt_f32_e32 vcc, 0, v191
	v_exp_f32_e32 v122, v122
	v_pk_fma_f32 v[158:159], v[156:157], s[58:59], v[120:121] op_sel_hi:[1,0,0]
	v_exp_f32_e32 v123, v123
	v_pk_fma_f32 v[158:159], v[156:157], v[158:159], s[66:67] op_sel_hi:[1,1,0]
	v_pk_mul_f32 v[116:117], v[116:117], v[154:155]
	v_pk_fma_f32 v[158:159], v[156:157], v[158:159], s[68:69] op_sel_hi:[1,1,0]
	v_cndmask_b32_e64 v125, v131, v135, s[38:39]
	v_pk_fma_f32 v[158:159], v[156:157], v[158:159], s[72:73] op_sel_hi:[1,1,0]
	v_pk_mul_f32 v[106:107], v[106:107], v[154:155]
	v_pk_mul_f32 v[156:157], v[156:157], v[158:159]
	v_pk_mul_f32 v[104:105], v[104:105], v[154:155]
	v_pk_mul_f32 v[122:123], v[122:123], v[156:157]
	v_pk_mul_f32 v[102:103], v[102:103], v[154:155]
	v_pk_mul_f32 v[156:157], v[190:191], v[122:123]
	v_pk_fma_f32 v[122:123], v[190:191], v[122:123], v[190:191] neg_lo:[1,0,0] neg_hi:[1,0,0]
	v_pk_mul_f32 v[100:101], v[100:101], v[154:155]
	v_cndmask_b32_e32 v123, v123, v157, vcc
	v_cmp_gt_f32_e32 vcc, 0, v190
	v_and_b32_e32 v157, 0x7fffffff, v189
	v_pk_mul_f32 v[112:113], v[112:113], v[184:185]
	v_cndmask_b32_e32 v122, v122, v156, vcc
	v_and_b32_e32 v156, 0x7fffffff, v188
	v_pk_fma_f32 v[156:157], v[156:157], s[56:57], 1.0 op_sel_hi:[1,0,0]
	v_pk_mul_f32 v[118:119], v[118:119], v[122:123]
	v_rcp_f32_e32 v156, v156
	v_rcp_f32_e32 v157, v157
	v_pk_mul_f32 v[122:123], v[188:189], v[188:189]
	v_cmp_gt_f32_e32 vcc, 0, v189
	v_pk_mul_f32 v[122:123], v[122:123], s[54:55] op_sel_hi:[1,0]
	v_pk_fma_f32 v[158:159], v[156:157], s[58:59], v[120:121] op_sel_hi:[1,0,0]
	v_exp_f32_e32 v122, v122
	v_exp_f32_e32 v123, v123
	v_pk_fma_f32 v[158:159], v[156:157], v[158:159], s[66:67] op_sel_hi:[1,1,0]
	v_pk_mul_f32 v[114:115], v[114:115], v[184:185]
	v_pk_fma_f32 v[158:159], v[156:157], v[158:159], s[68:69] op_sel_hi:[1,1,0]
	v_pk_mul_f32 v[108:109], v[108:109], v[150:151]
	v_pk_fma_f32 v[158:159], v[156:157], v[158:159], s[72:73] op_sel_hi:[1,1,0]
	v_cndmask_b32_e64 v185, v104, v108, s[42:43]
	v_pk_mul_f32 v[156:157], v[156:157], v[158:159]
	v_cndmask_b32_e64 v159, v131, v107, s[42:43]
	v_pk_mul_f32 v[122:123], v[122:123], v[156:157]
	v_cndmask_b32_e64 v186, v105, v109, s[42:43]
	v_pk_mul_f32 v[156:157], v[188:189], v[122:123]
	v_pk_fma_f32 v[122:123], v[188:189], v[122:123], v[188:189] neg_lo:[1,0,0] neg_hi:[1,0,0]
	v_cndmask_b32_e64 v187, v108, v104, s[38:39]
	v_cndmask_b32_e32 v123, v123, v157, vcc
	v_cmp_gt_f32_e32 vcc, 0, v188
	v_cndmask_b32_e64 v157, v130, v106, s[42:43]
	v_cndmask_b32_e64 v188, v109, v105, s[38:39]
	v_cndmask_b32_e32 v122, v122, v156, vcc
	v_pk_mul_f32 v[122:123], v[116:117], v[122:123]
	v_cvt_pk_bf16_f32 v117, v118, v119
	v_cndmask_b32_e64 v119, v128, v132, s[38:39]
	v_cvt_pk_bf16_f32 v116, v122, v123
	v_cndmask_b32_e64 v122, v129, v133, s[38:39]
	v_mov_b32_dpp v118, v119 row_ror:1 row_mask:0xf bank_mask:0xf
	v_cndmask_b32_e64 v123, v130, v134, s[38:39]
	v_mad_u64_u32 v[132:133], s[0:1], v182, s65, v[176:177]
	v_mov_b32_dpp v119, v122 row_ror:1 row_mask:0xf bank_mask:0xf
	v_mov_b32_e32 v133, v165
	v_mov_b32_dpp v122, v123 row_ror:1 row_mask:0xf bank_mask:0xf
	v_add_u32_e32 v164, 0xb000, v132
	v_mov_b32_dpp v156, v157 row_ror:15 row_mask:0xf bank_mask:0xf
	v_mov_b32_dpp v123, v125 row_ror:1 row_mask:0xf bank_mask:0xf
	v_pk_fma_f32 v[122:123], v[46:47], v[122:123], v[58:59]
	v_pk_fma_f32 v[122:123], v[130:131], v[50:51], v[122:123]
	v_lshl_add_u64 v[134:135], v[132:133], 1, s[28:29]
	v_lshl_add_u64 v[132:133], v[164:165], 1, s[28:29]
	v_mov_b32_dpp v157, v159 row_ror:15 row_mask:0xf bank_mask:0xf
	v_cndmask_b32_e64 v159, v106, v130, s[38:39]
	v_cndmask_b32_e64 v164, v107, v131, s[38:39]
	v_cndmask_b32_e64 v131, v128, v104, s[42:43]
	v_pk_fma_f32 v[118:119], v[44:45], v[118:119], v[56:57]
	v_pk_fma_f32 v[122:123], v[54:55], v[156:157], v[122:123]
	v_mov_b32_dpp v130, v131 row_ror:15 row_mask:0xf bank_mask:0xf
	v_cndmask_b32_e64 v156, v129, v105, s[42:43]
	v_pk_fma_f32 v[118:119], v[128:129], v[48:49], v[118:119]
	v_and_b32_e32 v155, 0x7fffffff, v123
	v_mov_b32_dpp v131, v156 row_ror:15 row_mask:0xf bank_mask:0xf
	v_pk_fma_f32 v[118:119], v[52:53], v[130:131], v[118:119]
	v_and_b32_e32 v154, 0x7fffffff, v122
	v_and_b32_e32 v131, 0x7fffffff, v119
	v_and_b32_e32 v130, 0x7fffffff, v118
	v_pk_fma_f32 v[130:131], v[130:131], s[56:57], 1.0 op_sel_hi:[1,0,0]
	v_pk_fma_f32 v[154:155], v[154:155], s[56:57], 1.0 op_sel_hi:[1,0,0]
	v_rcp_f32_e32 v130, v130
	v_rcp_f32_e32 v131, v131
	v_rcp_f32_e32 v154, v154
	v_rcp_f32_e32 v155, v155
	v_cmp_gt_f32_e32 vcc, 0, v119
	v_pk_fma_f32 v[156:157], v[130:131], s[58:59], v[120:121] op_sel_hi:[1,0,0]
	v_pk_mul_f32 v[110:111], v[110:111], v[150:151]
	v_pk_fma_f32 v[156:157], v[130:131], v[156:157], s[66:67] op_sel_hi:[1,1,0]
	v_cndmask_b32_e64 v182, v106, v110, s[42:43]
	v_pk_fma_f32 v[156:157], v[130:131], v[156:157], s[68:69] op_sel_hi:[1,1,0]
	v_cndmask_b32_e64 v184, v107, v111, s[42:43]
	v_pk_fma_f32 v[156:157], v[130:131], v[156:157], s[72:73] op_sel_hi:[1,1,0]
	v_cndmask_b32_e64 v125, v108, 0, s[42:43]
	v_pk_mul_f32 v[130:131], v[130:131], v[156:157]
	v_cndmask_b32_e64 v156, v104, v128, s[38:39]
	v_cndmask_b32_e64 v157, v105, v129, s[38:39]
	v_pk_mul_f32 v[128:129], v[118:119], v[118:119]
	v_cndmask_b32_e64 v158, v109, 0, s[42:43]
	v_pk_mul_f32 v[128:129], v[128:129], s[54:55] op_sel_hi:[1,0]
	v_pk_mul_f32 v[96:97], v[96:97], v[150:151]
	v_exp_f32_e32 v128, v128
	v_exp_f32_e32 v129, v129
	v_pk_mul_f32 v[98:99], v[98:99], v[150:151]
	v_pk_mul_f32 v[128:129], v[128:129], v[130:131]
	s_nop 0
	v_pk_mul_f32 v[130:131], v[118:119], v[128:129]
	v_pk_fma_f32 v[128:129], v[118:119], v[128:129], v[118:119] neg_lo:[1,0,0] neg_hi:[1,0,0]
	s_nop 0
	v_cndmask_b32_e32 v119, v129, v131, vcc
	v_cmp_gt_f32_e32 vcc, 0, v118
	s_nop 1
	v_cndmask_b32_e32 v118, v128, v130, vcc
	v_pk_mul_f32 v[130:131], v[122:123], v[122:123]
	v_pk_fma_f32 v[128:129], v[154:155], s[58:59], v[120:121] op_sel_hi:[1,0,0]
	v_pk_mul_f32 v[130:131], v[130:131], s[54:55] op_sel_hi:[1,0]
	v_pk_fma_f32 v[128:129], v[154:155], v[128:129], s[66:67] op_sel_hi:[1,1,0]
	v_exp_f32_e32 v130, v130
	v_exp_f32_e32 v131, v131
	v_pk_fma_f32 v[128:129], v[154:155], v[128:129], s[68:69] op_sel_hi:[1,1,0]
	v_cmp_gt_f32_e32 vcc, 0, v123
	v_pk_fma_f32 v[128:129], v[154:155], v[128:129], s[72:73] op_sel_hi:[1,1,0]
	v_pk_mul_f32 v[112:113], v[112:113], v[118:119]
	v_pk_mul_f32 v[128:129], v[154:155], v[128:129]
	s_nop 0
	v_pk_mul_f32 v[128:129], v[130:131], v[128:129]
	s_nop 0
	v_pk_mul_f32 v[130:131], v[122:123], v[128:129]
	v_pk_fma_f32 v[128:129], v[122:123], v[128:129], v[122:123] neg_lo:[1,0,0] neg_hi:[1,0,0]
	s_nop 0
	v_cndmask_b32_e32 v123, v129, v131, vcc
	v_cmp_gt_f32_e32 vcc, 0, v122
	s_nop 1
	v_cndmask_b32_e32 v122, v128, v130, vcc
	v_cvt_pk_bf16_f32 v128, v112, v113
	v_pk_mul_f32 v[114:115], v[114:115], v[122:123]
	v_mov_b32_dpp v112, v156 row_ror:1 row_mask:0xf bank_mask:0xf
	v_mov_b32_dpp v113, v157 row_ror:1 row_mask:0xf bank_mask:0xf
	v_cvt_pk_bf16_f32 v129, v114, v115
	v_pk_fma_f32 v[112:113], v[44:45], v[112:113], v[56:57]
	v_pk_fma_f32 v[104:105], v[104:105], v[48:49], v[112:113]
	v_mov_b32_dpp v114, v185 row_ror:15 row_mask:0xf bank_mask:0xf
	v_mov_b32_dpp v115, v186 row_ror:15 row_mask:0xf bank_mask:0xf
	v_pk_fma_f32 v[104:105], v[52:53], v[114:115], v[104:105]
	v_and_b32_e32 v115, 0x7fffffff, v105
	v_and_b32_e32 v114, 0x7fffffff, v104
	v_pk_fma_f32 v[114:115], v[114:115], s[56:57], 1.0 op_sel_hi:[1,0,0]
	v_pk_mul_f32 v[122:123], v[104:105], v[104:105]
	v_rcp_f32_e32 v114, v114
	v_rcp_f32_e32 v115, v115
	v_pk_mul_f32 v[122:123], v[122:123], s[54:55] op_sel_hi:[1,0]
	v_mov_b32_dpp v112, v159 row_ror:1 row_mask:0xf bank_mask:0xf
	v_pk_fma_f32 v[118:119], v[114:115], s[58:59], v[120:121] op_sel_hi:[1,0,0]
	v_mov_b32_dpp v113, v164 row_ror:1 row_mask:0xf bank_mask:0xf
	v_pk_fma_f32 v[118:119], v[114:115], v[118:119], s[66:67] op_sel_hi:[1,1,0]
	v_exp_f32_e32 v122, v122
	v_pk_fma_f32 v[118:119], v[114:115], v[118:119], s[68:69] op_sel_hi:[1,1,0]
	v_exp_f32_e32 v123, v123
	v_pk_fma_f32 v[118:119], v[114:115], v[118:119], s[72:73] op_sel_hi:[1,1,0]
	v_pk_fma_f32 v[112:113], v[46:47], v[112:113], v[58:59]
	v_pk_mul_f32 v[114:115], v[114:115], v[118:119]
	v_pk_fma_f32 v[112:113], v[106:107], v[50:51], v[112:113]
	v_mov_b32_dpp v118, v182 row_ror:15 row_mask:0xf bank_mask:0xf
	v_mov_b32_dpp v119, v184 row_ror:15 row_mask:0xf bank_mask:0xf
	v_pk_fma_f32 v[112:113], v[54:55], v[118:119], v[112:113]
	v_pk_mul_f32 v[114:115], v[122:123], v[114:115]
	v_and_b32_e32 v123, 0x7fffffff, v113
	v_and_b32_e32 v122, 0x7fffffff, v112
	v_pk_fma_f32 v[122:123], v[122:123], s[56:57], 1.0 op_sel_hi:[1,0,0]
	v_pk_mul_f32 v[118:119], v[104:105], v[114:115]
	v_rcp_f32_e32 v122, v122
	v_rcp_f32_e32 v123, v123
	v_pk_fma_f32 v[114:115], v[104:105], v[114:115], v[104:105] neg_lo:[1,0,0] neg_hi:[1,0,0]
	v_cmp_gt_f32_e32 vcc, 0, v105
	global_store_dwordx4 v[134:135], v[126:129], off nt
	v_cndmask_b32_e64 v107, v111, v107, s[38:39]
	v_cndmask_b32_e32 v105, v115, v119, vcc
	v_cmp_gt_f32_e32 vcc, 0, v104
	s_nop 1
	v_cndmask_b32_e32 v104, v114, v118, vcc
	v_pk_mul_f32 v[118:119], v[112:113], v[112:113]
	v_pk_fma_f32 v[114:115], v[122:123], s[58:59], v[120:121] op_sel_hi:[1,0,0]
	v_pk_mul_f32 v[118:119], v[118:119], s[54:55] op_sel_hi:[1,0]
	v_pk_fma_f32 v[114:115], v[122:123], v[114:115], s[66:67] op_sel_hi:[1,1,0]
	v_exp_f32_e32 v118, v118
	v_exp_f32_e32 v119, v119
	v_pk_fma_f32 v[114:115], v[122:123], v[114:115], s[68:69] op_sel_hi:[1,1,0]
	v_cmp_gt_f32_e32 vcc, 0, v113
	v_pk_fma_f32 v[114:115], v[122:123], v[114:115], s[72:73] op_sel_hi:[1,1,0]
	v_pk_mul_f32 v[100:101], v[100:101], v[104:105]
	v_pk_mul_f32 v[114:115], v[122:123], v[114:115]
	v_cndmask_b32_e64 v105, v110, v106, s[38:39]
	v_pk_mul_f32 v[114:115], v[118:119], v[114:115]
	v_pk_mul_f32 v[118:119], v[112:113], v[114:115]
	v_pk_fma_f32 v[114:115], v[112:113], v[114:115], v[112:113] neg_lo:[1,0,0] neg_hi:[1,0,0]
	v_mov_b32_dpp v104, v105 row_ror:1 row_mask:0xf bank_mask:0xf
	v_cndmask_b32_e32 v113, v115, v119, vcc
	v_cmp_gt_f32_e32 vcc, 0, v112
	v_cndmask_b32_e64 v105, v110, 0, s[42:43]
	v_mov_b32_e32 v106, 0
	v_cndmask_b32_e32 v112, v114, v118, vcc
	v_pk_mul_f32 v[102:103], v[102:103], v[112:113]
	v_cvt_pk_bf16_f32 v118, v100, v101
	v_cvt_pk_bf16_f32 v119, v102, v103
	global_store_dwordx4 v[132:133], v[116:119], off nt
	v_mov_b32_dpp v106, v105 row_ror:15 row_mask:0xf bank_mask:0xf
	v_mov_b32_dpp v105, v107 row_ror:1 row_mask:0xf bank_mask:0xf
	v_cndmask_b32_e64 v112, v111, 0, s[42:43]
	v_mov_b32_dpp v100, v187 row_ror:1 row_mask:0xf bank_mask:0xf
	v_mov_b32_dpp v102, v125 row_ror:15 row_mask:0xf bank_mask:0xf
	v_mov_b32_dpp v101, v188 row_ror:1 row_mask:0xf bank_mask:0xf
	v_mov_b32_dpp v103, v158 row_ror:15 row_mask:0xf bank_mask:0xf
	v_mov_b32_dpp v107, v112 row_ror:15 row_mask:0xf bank_mask:0xf
	s_and_saveexec_b64 s[0:1], s[36:37]
	s_cbranch_execnz .LBB0_737
	s_or_b64 exec, exec, s[0:1]
	s_and_saveexec_b64 s[0:1], s[74:75]
	s_cbranch_execnz .LBB0_738

.LBB0_720:
	s_or_b64 exec, exec, s[0:1]
	v_fmamk_f32 v96, v183, 0x3a800000, v239
	v_cmp_gt_f32_e32 vcc, s33, v96
	v_mul_f32_e32 v97, 0x4b800000, v96
	v_mov_b32_e32 v128, 0
	v_cndmask_b32_e32 v96, v96, v97, vcc
	v_rsq_f32_e32 v96, v96
	v_mov_b32_e32 v129, 0
	v_mul_f32_e32 v97, 0x45800000, v96
	v_cndmask_b32_e32 v120, v96, v97, vcc
	v_fmamk_f32 v96, v181, 0x3a800000, v239
	v_cmp_gt_f32_e32 vcc, s33, v96
	v_mul_f32_e32 v97, 0x4b800000, v96
	v_pk_mul_f32 v[122:123], v[92:93], v[120:121] op_sel_hi:[1,0]
	v_cndmask_b32_e32 v96, v96, v97, vcc
	v_rsq_f32_e32 v96, v96
	v_cndmask_b32_e64 v92, v122, 0, s[38:39]
	v_pk_mul_f32 v[132:133], v[94:95], v[120:121] op_sel_hi:[1,0]
	v_mul_f32_e32 v97, 0x45800000, v96
	v_cndmask_b32_e32 v96, v96, v97, vcc
	v_pk_mul_f32 v[98:99], v[88:89], v[96:97] op_sel_hi:[1,0]
	v_mov_b32_dpp v126, v92 row_ror:1 row_mask:0xf bank_mask:0xf
	v_cndmask_b32_e64 v88, v122, v98, s[42:43]
	v_pk_mul_f32 v[92:93], v[90:91], v[96:97] op_sel_hi:[1,0]
	v_mov_b32_e32 v136, 0
	v_mov_b32_dpp v128, v88 row_ror:15 row_mask:0xf bank_mask:0xf
	v_cndmask_b32_e64 v88, v123, 0, s[38:39]
	v_mov_b32_e32 v135, 0
	s_add_i32 s51, s51, 12
	v_mov_b32_dpp v127, v88 row_ror:1 row_mask:0xf bank_mask:0xf
	v_cndmask_b32_e64 v88, v123, v99, s[42:43]
	v_mov_b32_e32 v137, 0
	v_add_u32_e32 v91, s51, v234
	v_mov_b32_dpp v129, v88 row_ror:15 row_mask:0xf bank_mask:0xf
	v_cndmask_b32_e64 v88, v132, 0, s[38:39]
	s_nop 1
	v_mov_b32_dpp v134, v88 row_ror:1 row_mask:0xf bank_mask:0xf
	v_cndmask_b32_e64 v88, v132, v92, s[42:43]
	s_nop 1
	v_mov_b32_dpp v136, v88 row_ror:15 row_mask:0xf bank_mask:0xf
	v_cndmask_b32_e64 v88, v133, 0, s[38:39]
	s_nop 1
	v_mov_b32_dpp v135, v88 row_ror:1 row_mask:0xf bank_mask:0xf
	v_cndmask_b32_e64 v88, v133, v93, s[42:43]
	s_nop 1
	v_mov_b32_dpp v137, v88 row_ror:15 row_mask:0xf bank_mask:0xf
	s_and_saveexec_b64 s[0:1], s[70:71]
	s_cbranch_execz .LBB0_722
	v_mad_u64_u32 v[94:95], s[22:23], v91, s65, v[176:177]
	v_mov_b32_e32 v95, v165
	v_cvt_pk_bf16_f32 v88, v122, v123
	v_cvt_pk_bf16_f32 v89, v132, v133
	v_lshl_add_u64 v[94:95], v[94:95], 1, s[30:31]
	global_store_dwordx2 v[94:95], v[88:89], off

.LBB0_724:
	s_or_b64 exec, exec, s[0:1]
	v_fmamk_f32 v84, v175, 0x3a800000, v239
	v_cmp_gt_f32_e32 vcc, s33, v84
	v_mul_f32_e32 v85, 0x4b800000, v84
	v_mov_b32_e32 v114, 0
	v_cndmask_b32_e32 v84, v84, v85, vcc
	v_rsq_f32_e32 v84, v84
	v_mov_b32_e32 v116, 0
	v_mul_f32_e32 v85, 0x45800000, v84
	v_cndmask_b32_e32 v90, v84, v85, vcc
	v_fmamk_f32 v84, v179, 0x3a800000, v239
	v_cmp_gt_f32_e32 vcc, s33, v84
	v_mul_f32_e32 v85, 0x4b800000, v84
	v_pk_mul_f32 v[94:95], v[60:61], v[90:91] op_sel_hi:[1,0]
	v_cndmask_b32_e32 v84, v84, v85, vcc
	v_rsq_f32_e32 v84, v84
	v_cndmask_b32_e64 v60, v98, v94, s[42:43]
	v_mul_f32_e32 v85, 0x45800000, v84
	v_cndmask_b32_e32 v86, v84, v85, vcc
	v_cndmask_b32_e64 v84, v98, v122, s[38:39]
	v_mov_b32_dpp v116, v60 row_ror:15 row_mask:0xf bank_mask:0xf
	v_cndmask_b32_e64 v60, v99, v95, s[42:43]
	v_mov_b32_dpp v114, v84 row_ror:1 row_mask:0xf bank_mask:0xf
	v_cndmask_b32_e64 v84, v99, v123, s[38:39]
	v_mov_b32_dpp v117, v60 row_ror:15 row_mask:0xf bank_mask:0xf
	v_cndmask_b32_e64 v60, v94, v98, s[38:39]
	v_mov_b32_dpp v115, v84 row_ror:1 row_mask:0xf bank_mask:0xf
	v_cndmask_b32_e64 v84, v92, v132, s[38:39]
	v_mov_b32_e32 v104, 0
	v_mov_b32_e32 v106, 0
	v_mov_b32_dpp v102, v84 row_ror:1 row_mask:0xf bank_mask:0xf
	v_cndmask_b32_e64 v84, v93, v133, s[38:39]
	v_mov_b32_dpp v104, v60 row_ror:1 row_mask:0xf bank_mask:0xf
	v_mov_b32_e32 v105, 0
	v_mov_b32_dpp v103, v84 row_ror:1 row_mask:0xf bank_mask:0xf
	v_pk_mul_f32 v[84:85], v[64:65], v[86:87] op_sel_hi:[1,0]
	v_cndmask_b32_e64 v60, v94, v84, s[42:43]
	v_pk_mul_f32 v[100:101], v[62:63], v[90:91] op_sel_hi:[1,0]
	v_mov_b32_e32 v112, 0
	v_mov_b32_dpp v106, v60 row_ror:15 row_mask:0xf bank_mask:0xf
	v_cndmask_b32_e64 v60, v95, v99, s[38:39]
	v_mov_b32_e32 v113, 0
	v_pk_mul_f32 v[64:65], v[66:67], v[86:87] op_sel_hi:[1,0]
	v_mov_b32_dpp v105, v60 row_ror:1 row_mask:0xf bank_mask:0xf
	v_cndmask_b32_e64 v60, v95, v85, s[42:43]
	v_mov_b32_e32 v108, 0
	v_mov_b32_e32 v110, 0
	v_mov_b32_dpp v107, v60 row_ror:15 row_mask:0xf bank_mask:0xf
	v_cndmask_b32_e64 v60, v92, v100, s[42:43]
	v_mov_b32_e32 v109, 0
	v_mov_b32_e32 v111, 0
	v_mov_b32_dpp v112, v60 row_ror:15 row_mask:0xf bank_mask:0xf
	v_cndmask_b32_e64 v60, v93, v101, s[42:43]
	v_cndmask_b32_e64 v61, v84, v94, s[38:39]
	v_mov_b32_e32 v62, 0
	v_mov_b32_dpp v113, v60 row_ror:15 row_mask:0xf bank_mask:0xf
	v_cndmask_b32_e64 v60, v100, v92, s[38:39]
	v_cndmask_b32_e64 v63, v85, v95, s[38:39]
	v_cndmask_b32_e64 v66, v85, 0, s[42:43]
	v_mov_b32_dpp v108, v60 row_ror:1 row_mask:0xf bank_mask:0xf
	v_cndmask_b32_e64 v60, v100, v64, s[42:43]
	v_cndmask_b32_e64 v67, v64, v100, s[38:39]
	v_mov_b32_e32 v88, 0
	v_mov_b32_dpp v110, v60 row_ror:15 row_mask:0xf bank_mask:0xf
	v_cndmask_b32_e64 v60, v101, v93, s[38:39]
	v_cndmask_b32_e64 v87, v65, v101, s[38:39]
	v_mov_b32_e32 v89, 0
	v_mov_b32_dpp v109, v60 row_ror:1 row_mask:0xf bank_mask:0xf
	v_cndmask_b32_e64 v60, v101, v65, s[42:43]
	v_add_u32_e32 v125, s51, v233
	s_nop 0
	v_mov_b32_dpp v111, v60 row_ror:15 row_mask:0xf bank_mask:0xf
	s_nop 1
	v_mov_b32_dpp v60, v61 row_ror:1 row_mask:0xf bank_mask:0xf
	v_cndmask_b32_e64 v61, v84, 0, s[42:43]
	s_nop 1
	v_mov_b32_dpp v62, v61 row_ror:15 row_mask:0xf bank_mask:0xf
	s_nop 1
	v_mov_b32_dpp v61, v63 row_ror:1 row_mask:0xf bank_mask:0xf
	s_nop 1
	v_mov_b32_dpp v63, v66 row_ror:15 row_mask:0xf bank_mask:0xf
	s_nop 1
	v_mov_b32_dpp v66, v67 row_ror:1 row_mask:0xf bank_mask:0xf
	v_cndmask_b32_e64 v67, v64, 0, s[42:43]
	s_nop 1
	v_mov_b32_dpp v88, v67 row_ror:15 row_mask:0xf bank_mask:0xf
	s_nop 1
	v_mov_b32_dpp v67, v87 row_ror:1 row_mask:0xf bank_mask:0xf
	v_cndmask_b32_e64 v87, v65, 0, s[42:43]
	s_nop 1
	v_mov_b32_dpp v89, v87 row_ror:15 row_mask:0xf bank_mask:0xf
	s_and_saveexec_b64 s[0:1], s[74:75]
	s_cbranch_execz .LBB0_726
	v_mad_u64_u32 v[140:141], s[22:23], v125, s65, v[176:177]
	v_mov_b32_e32 v141, v165
	v_cvt_pk_bf16_f32 v138, v84, v85
	v_cvt_pk_bf16_f32 v139, v64, v65
	v_lshl_add_u64 v[140:141], v[140:141], 1, s[30:31]
	global_store_dwordx2 v[140:141], v[138:139], off

.LBB0_728:
	s_or_b64 exec, exec, s[0:1]
	v_mov_b32_e32 v97, v96
	v_pk_mul_f32 v[40:41], v[40:41], v[120:121]
	v_pk_mul_f32 v[36:37], v[36:37], v[96:97]
	v_cndmask_b32_e64 v138, v40, 0, s[38:39]
	v_mov_b32_e32 v140, 0
	v_mov_b32_e32 v142, 0
	v_mov_b32_e32 v141, 0
	v_mov_b32_dpp v140, v138 row_ror:1 row_mask:0xf bank_mask:0xf
	v_pk_mul_f32 v[138:139], v[28:29], v[120:121]
	v_cndmask_b32_e64 v28, v40, v36, s[42:43]
	v_mov_b32_e32 v143, 0
	v_pk_mul_f32 v[30:31], v[30:31], v[120:121]
	v_mov_b32_dpp v142, v28 row_ror:15 row_mask:0xf bank_mask:0xf
	v_cndmask_b32_e64 v28, v41, 0, s[38:39]
	s_nop 1
	v_mov_b32_dpp v141, v28 row_ror:1 row_mask:0xf bank_mask:0xf
	v_cndmask_b32_e64 v28, v41, v37, s[42:43]
	s_nop 1
	v_mov_b32_dpp v143, v28 row_ror:15 row_mask:0xf bank_mask:0xf
	v_pk_mul_f32 v[28:29], v[38:39], v[96:97]
	v_pk_mul_f32 v[38:39], v[42:43], v[120:121]
	v_cndmask_b32_e64 v43, v38, 0, s[38:39]
	v_mov_b32_e32 v120, 0
	v_cndmask_b32_e64 v121, v39, 0, s[38:39]
	v_mov_b32_dpp v42, v43 row_ror:1 row_mask:0xf bank_mask:0xf
	v_cndmask_b32_e64 v43, v38, v28, s[42:43]
	v_cndmask_b32_e64 v144, v39, v29, s[42:43]
	s_nop 0
	v_mov_b32_dpp v120, v43 row_ror:15 row_mask:0xf bank_mask:0xf
	s_nop 1
	v_mov_b32_dpp v43, v121 row_ror:1 row_mask:0xf bank_mask:0xf
	s_nop 1
	v_mov_b32_dpp v121, v144 row_ror:15 row_mask:0xf bank_mask:0xf
	s_and_saveexec_b64 s[0:1], s[40:41]
	s_cbranch_execnz .LBB0_739
	s_or_b64 exec, exec, s[0:1]
	s_and_saveexec_b64 s[0:1], s[70:71]
	s_cbranch_execnz .LBB0_740

.LBB0_732:
	s_or_b64 exec, exec, s[0:1]
	v_pk_fma_f32 v[30:31], v[68:69], v[114:115], v[80:81]
	v_pk_mul_f32 v[42:43], v[24:25], v[96:97]
	v_pk_fma_f32 v[30:31], v[72:73], v[98:99], v[30:31]
	v_pk_mul_f32 v[26:27], v[26:27], v[96:97]
	v_pk_fma_f32 v[30:31], v[76:77], v[116:117], v[30:31]
	v_mov_b32_e32 v91, v90
	v_and_b32_e32 v25, 0x7fffffff, v31
	v_and_b32_e32 v24, 0x7fffffff, v30
	v_pk_fma_f32 v[24:25], v[24:25], s[56:57], 1.0 op_sel_hi:[1,0,0]
	v_pk_mul_f32 v[22:23], v[22:23], v[90:91]
	v_rcp_f32_e32 v98, v24
	v_rcp_f32_e32 v99, v25
	v_pk_fma_f32 v[24:25], v[70:71], v[102:103], v[82:83]
	v_pk_mul_f32 v[20:21], v[20:21], v[90:91]
	v_pk_fma_f32 v[92:93], v[74:75], v[92:93], v[24:25]
	v_mov_b64_e32 v[24:25], s[64:65]
	v_pk_fma_f32 v[102:103], v[98:99], s[58:59], v[24:25] op_sel_hi:[1,0,0]
	v_pk_fma_f32 v[92:93], v[78:79], v[112:113], v[92:93]
	v_pk_fma_f32 v[102:103], v[98:99], v[102:103], s[66:67] op_sel_hi:[1,1,0]
	v_cmp_gt_f32_e32 vcc, 0, v93
	v_pk_fma_f32 v[102:103], v[98:99], v[102:103], s[68:69] op_sel_hi:[1,1,0]
	v_pk_mul_f32 v[10:11], v[10:11], v[90:91]
	v_pk_fma_f32 v[102:103], v[98:99], v[102:103], s[72:73] op_sel_hi:[1,1,0]
	v_pk_mul_f32 v[8:9], v[8:9], v[90:91]
	v_pk_mul_f32 v[98:99], v[98:99], v[102:103]
	v_pk_fma_f32 v[102:103], v[68:69], v[104:105], v[80:81]
	v_and_b32_e32 v105, 0x7fffffff, v93
	v_and_b32_e32 v104, 0x7fffffff, v92
	v_pk_fma_f32 v[104:105], v[104:105], s[56:57], 1.0 op_sel_hi:[1,0,0]
	v_pk_fma_f32 v[94:95], v[72:73], v[94:95], v[102:103]
	v_rcp_f32_e32 v104, v104
	v_rcp_f32_e32 v105, v105
	v_pk_fma_f32 v[102:103], v[70:71], v[108:109], v[82:83]
	v_pk_fma_f32 v[94:95], v[76:77], v[106:107], v[94:95]
	v_pk_fma_f32 v[100:101], v[74:75], v[100:101], v[102:103]
	v_pk_mul_f32 v[102:103], v[92:93], v[92:93]
	v_pk_fma_f32 v[106:107], v[104:105], s[58:59], v[24:25] op_sel_hi:[1,0,0]
	v_pk_mul_f32 v[102:103], v[102:103], s[54:55] op_sel_hi:[1,0]
	v_pk_fma_f32 v[106:107], v[104:105], v[106:107], s[66:67] op_sel_hi:[1,1,0]
	v_exp_f32_e32 v102, v102
	v_exp_f32_e32 v103, v103
	v_pk_fma_f32 v[106:107], v[104:105], v[106:107], s[68:69] op_sel_hi:[1,1,0]
	v_pk_fma_f32 v[100:101], v[78:79], v[110:111], v[100:101]
	v_pk_fma_f32 v[106:107], v[104:105], v[106:107], s[72:73] op_sel_hi:[1,1,0]
	v_pk_mul_f32 v[6:7], v[6:7], v[90:91]
	v_pk_mul_f32 v[104:105], v[104:105], v[106:107]
	v_pk_mul_f32 v[106:107], v[30:31], v[30:31]
	v_pk_mul_f32 v[102:103], v[102:103], v[104:105]
	v_pk_mul_f32 v[106:107], v[106:107], s[54:55] op_sel_hi:[1,0]
	v_pk_mul_f32 v[104:105], v[92:93], v[102:103]
	v_exp_f32_e32 v106, v106
	v_exp_f32_e32 v107, v107
	v_pk_fma_f32 v[102:103], v[92:93], v[102:103], v[92:93] neg_lo:[1,0,0] neg_hi:[1,0,0]
	v_pk_mul_f32 v[4:5], v[4:5], v[90:91]
	v_cndmask_b32_e32 v93, v103, v105, vcc
	v_cmp_gt_f32_e32 vcc, 0, v92
	v_pk_mul_f32 v[0:1], v[0:1], v[86:87]
	v_pk_mul_f32 v[2:3], v[2:3], v[86:87]
	v_cndmask_b32_e32 v92, v102, v104, vcc
	v_pk_mul_f32 v[26:27], v[26:27], v[92:93]
	v_pk_mul_f32 v[92:93], v[106:107], v[98:99]
	v_cmp_gt_f32_e32 vcc, 0, v31
	v_pk_mul_f32 v[98:99], v[30:31], v[92:93]
	v_pk_fma_f32 v[92:93], v[30:31], v[92:93], v[30:31] neg_lo:[1,0,0] neg_hi:[1,0,0]
	v_cvt_pk_bf16_f32 v27, v26, v27
	v_cndmask_b32_e32 v31, v93, v99, vcc
	v_cmp_gt_f32_e32 vcc, 0, v30
	s_nop 1
	v_cndmask_b32_e32 v30, v92, v98, vcc
	v_pk_mul_f32 v[30:31], v[42:43], v[30:31]
	v_and_b32_e32 v43, 0x7fffffff, v101
	v_and_b32_e32 v42, 0x7fffffff, v100
	v_pk_fma_f32 v[42:43], v[42:43], s[56:57], 1.0 op_sel_hi:[1,0,0]
	v_cvt_pk_bf16_f32 v26, v30, v31
	v_rcp_f32_e32 v42, v42
	v_rcp_f32_e32 v43, v43
	v_pk_mul_f32 v[30:31], v[100:101], v[100:101]
	v_cmp_gt_f32_e32 vcc, 0, v101
	v_pk_mul_f32 v[30:31], v[30:31], s[54:55] op_sel_hi:[1,0]
	v_pk_fma_f32 v[92:93], v[42:43], s[58:59], v[24:25] op_sel_hi:[1,0,0]
	v_exp_f32_e32 v30, v30
	v_exp_f32_e32 v31, v31
	v_pk_fma_f32 v[92:93], v[42:43], v[92:93], s[66:67] op_sel_hi:[1,1,0]
	s_nop 0
	v_pk_fma_f32 v[92:93], v[42:43], v[92:93], s[68:69] op_sel_hi:[1,1,0]
	s_nop 0
	v_pk_fma_f32 v[92:93], v[42:43], v[92:93], s[72:73] op_sel_hi:[1,1,0]
	s_nop 0
	v_pk_mul_f32 v[42:43], v[42:43], v[92:93]
	s_nop 0
	v_pk_mul_f32 v[30:31], v[30:31], v[42:43]
	s_nop 0
	v_pk_mul_f32 v[42:43], v[100:101], v[30:31]
	v_pk_fma_f32 v[30:31], v[100:101], v[30:31], v[100:101] neg_lo:[1,0,0] neg_hi:[1,0,0]
	s_nop 0
	v_cndmask_b32_e32 v31, v31, v43, vcc
	v_cmp_gt_f32_e32 vcc, 0, v100
	v_and_b32_e32 v43, 0x7fffffff, v95
	s_nop 0
	v_cndmask_b32_e32 v30, v30, v42, vcc
	v_and_b32_e32 v42, 0x7fffffff, v94
	v_pk_fma_f32 v[42:43], v[42:43], s[56:57], 1.0 op_sel_hi:[1,0,0]
	v_pk_mul_f32 v[22:23], v[22:23], v[30:31]
	v_rcp_f32_e32 v42, v42
	v_rcp_f32_e32 v43, v43
	v_pk_mul_f32 v[30:31], v[94:95], v[94:95]
	v_cmp_gt_f32_e32 vcc, 0, v95
	v_pk_mul_f32 v[30:31], v[30:31], s[54:55] op_sel_hi:[1,0]
	v_pk_fma_f32 v[92:93], v[42:43], s[58:59], v[24:25] op_sel_hi:[1,0,0]
	v_exp_f32_e32 v30, v30
	v_exp_f32_e32 v31, v31
	v_pk_fma_f32 v[92:93], v[42:43], v[92:93], s[66:67] op_sel_hi:[1,1,0]
	s_nop 0
	v_pk_fma_f32 v[92:93], v[42:43], v[92:93], s[68:69] op_sel_hi:[1,1,0]
	s_nop 0
	v_pk_fma_f32 v[92:93], v[42:43], v[92:93], s[72:73] op_sel_hi:[1,1,0]
	s_nop 0
	v_pk_mul_f32 v[42:43], v[42:43], v[92:93]
	s_nop 0
	v_pk_mul_f32 v[30:31], v[30:31], v[42:43]
	s_nop 0
	v_pk_mul_f32 v[42:43], v[94:95], v[30:31]
	v_pk_fma_f32 v[30:31], v[94:95], v[30:31], v[94:95] neg_lo:[1,0,0] neg_hi:[1,0,0]
	s_nop 0
	v_cndmask_b32_e32 v31, v31, v43, vcc
	v_cmp_gt_f32_e32 vcc, 0, v94
	s_nop 1
	v_cndmask_b32_e32 v30, v30, v42, vcc
	v_pk_mul_f32 v[30:31], v[20:21], v[30:31]
	v_cvt_pk_bf16_f32 v21, v22, v23
	v_cndmask_b32_e64 v23, v36, v40, s[38:39]
	v_cvt_pk_bf16_f32 v20, v30, v31
	v_cndmask_b32_e64 v30, v37, v41, s[38:39]
	v_mov_b32_dpp v22, v23 row_ror:1 row_mask:0xf bank_mask:0xf
	v_cndmask_b32_e64 v31, v28, v38, s[38:39]
	v_pk_mul_f32 v[40:41], v[12:13], v[96:97]
	v_mov_b32_dpp v23, v30 row_ror:1 row_mask:0xf bank_mask:0xf
	v_mad_u64_u32 v[12:13], s[0:1], v174, s65, v[176:177]
	s_nop 0
	v_mov_b32_dpp v30, v31 row_ror:1 row_mask:0xf bank_mask:0xf
	v_cndmask_b32_e64 v38, v29, v39, s[38:39]
	v_mov_b32_e32 v13, v165
	v_lshl_add_u64 v[42:43], v[12:13], 1, s[28:29]
	v_mov_b32_dpp v31, v38 row_ror:1 row_mask:0xf bank_mask:0xf
	v_pk_mul_f32 v[38:39], v[14:15], v[96:97]
	v_pk_fma_f32 v[14:15], v[44:45], v[22:23], v[56:57]
	v_add_u32_e32 v164, 0xb000, v12
	v_pk_mul_f32 v[12:13], v[16:17], v[86:87]
	v_cndmask_b32_e64 v17, v28, v10, s[42:43]
	v_pk_fma_f32 v[22:23], v[36:37], v[48:49], v[14:15]
	v_pk_mul_f32 v[14:15], v[18:19], v[86:87]
	v_mov_b32_dpp v16, v17 row_ror:15 row_mask:0xf bank_mask:0xf
	v_cndmask_b32_e64 v18, v29, v11, s[42:43]
	v_pk_fma_f32 v[30:31], v[46:47], v[30:31], v[58:59]
	v_cndmask_b32_e64 v19, v36, v8, s[42:43]
	v_mov_b32_dpp v17, v18 row_ror:15 row_mask:0xf bank_mask:0xf
	v_pk_fma_f32 v[30:31], v[28:29], v[50:51], v[30:31]
	v_cndmask_b32_e64 v96, v10, v28, s[38:39]
	v_mov_b32_dpp v18, v19 row_ror:15 row_mask:0xf bank_mask:0xf
	v_cndmask_b32_e64 v28, v37, v9, s[42:43]
	v_cndmask_b32_e64 v97, v11, v29, s[38:39]
	v_pk_fma_f32 v[16:17], v[54:55], v[16:17], v[30:31]
	v_mov_b32_dpp v19, v28 row_ror:15 row_mask:0xf bank_mask:0xf
	v_pk_fma_f32 v[18:19], v[52:53], v[18:19], v[22:23]
	v_and_b32_e32 v31, 0x7fffffff, v17
	v_and_b32_e32 v23, 0x7fffffff, v19
	v_and_b32_e32 v22, 0x7fffffff, v18
	v_pk_fma_f32 v[22:23], v[22:23], s[56:57], 1.0 op_sel_hi:[1,0,0]
	v_and_b32_e32 v30, 0x7fffffff, v16
	v_rcp_f32_e32 v22, v22
	v_rcp_f32_e32 v23, v23
	v_pk_fma_f32 v[30:31], v[30:31], s[56:57], 1.0 op_sel_hi:[1,0,0]
	v_cmp_gt_f32_e32 vcc, 0, v19
	v_rcp_f32_e32 v30, v30
	v_pk_fma_f32 v[28:29], v[22:23], s[58:59], v[24:25] op_sel_hi:[1,0,0]
	v_rcp_f32_e32 v31, v31
	v_pk_fma_f32 v[28:29], v[22:23], v[28:29], s[66:67] op_sel_hi:[1,1,0]
	v_cndmask_b32_e64 v36, v8, v36, s[38:39]
	v_pk_fma_f32 v[28:29], v[22:23], v[28:29], s[68:69] op_sel_hi:[1,1,0]
	v_cndmask_b32_e64 v37, v9, v37, s[38:39]
	v_pk_fma_f32 v[28:29], v[22:23], v[28:29], s[72:73] op_sel_hi:[1,1,0]
	v_cndmask_b32_e64 v90, v8, v12, s[42:43]
	v_pk_mul_f32 v[22:23], v[22:23], v[28:29]
	v_pk_mul_f32 v[28:29], v[18:19], v[18:19]
	v_cndmask_b32_e64 v91, v9, v13, s[42:43]
	v_pk_mul_f32 v[28:29], v[28:29], s[54:55] op_sel_hi:[1,0]
	v_cndmask_b32_e64 v100, v12, v8, s[38:39]
	v_exp_f32_e32 v28, v28
	v_exp_f32_e32 v29, v29
	v_cndmask_b32_e64 v101, v13, v9, s[38:39]
	v_cndmask_b32_e64 v98, v10, v14, s[42:43]
	v_cndmask_b32_e64 v99, v11, v15, s[42:43]
	v_pk_mul_f32 v[22:23], v[28:29], v[22:23]
	v_lshl_add_u64 v[92:93], v[164:165], 1, s[28:29]
	v_pk_mul_f32 v[28:29], v[18:19], v[22:23]
	v_pk_fma_f32 v[22:23], v[18:19], v[22:23], v[18:19] neg_lo:[1,0,0] neg_hi:[1,0,0]
	v_cndmask_b32_e64 v94, v12, 0, s[42:43]
	v_cndmask_b32_e32 v19, v23, v29, vcc
	v_cmp_gt_f32_e32 vcc, 0, v18
	v_cndmask_b32_e64 v95, v13, 0, s[42:43]
	s_nop 0
	v_cndmask_b32_e32 v18, v22, v28, vcc
	v_pk_mul_f32 v[28:29], v[16:17], v[16:17]
	v_pk_fma_f32 v[22:23], v[30:31], s[58:59], v[24:25] op_sel_hi:[1,0,0]
	v_pk_mul_f32 v[28:29], v[28:29], s[54:55] op_sel_hi:[1,0]
	v_pk_fma_f32 v[22:23], v[30:31], v[22:23], s[66:67] op_sel_hi:[1,1,0]
	v_exp_f32_e32 v28, v28
	v_exp_f32_e32 v29, v29
	v_pk_fma_f32 v[22:23], v[30:31], v[22:23], s[68:69] op_sel_hi:[1,1,0]
	v_cmp_gt_f32_e32 vcc, 0, v17
	v_pk_fma_f32 v[22:23], v[30:31], v[22:23], s[72:73] op_sel_hi:[1,1,0]
	v_pk_mul_f32 v[18:19], v[40:41], v[18:19]
	v_pk_mul_f32 v[22:23], v[30:31], v[22:23]
	s_nop 0
	v_pk_mul_f32 v[22:23], v[28:29], v[22:23]
	s_nop 0
	v_pk_mul_f32 v[28:29], v[16:17], v[22:23]
	v_pk_fma_f32 v[22:23], v[16:17], v[22:23], v[16:17] neg_lo:[1,0,0] neg_hi:[1,0,0]
	s_nop 0
	v_cndmask_b32_e32 v17, v23, v29, vcc
	v_cmp_gt_f32_e32 vcc, 0, v16
	s_nop 1
	v_cndmask_b32_e32 v16, v22, v28, vcc
	v_pk_mul_f32 v[16:17], v[38:39], v[16:17]
	v_cvt_pk_bf16_f32 v28, v18, v19
	v_cvt_pk_bf16_f32 v29, v16, v17
	v_mov_b32_dpp v16, v36 row_ror:1 row_mask:0xf bank_mask:0xf
	v_mov_b32_dpp v17, v37 row_ror:1 row_mask:0xf bank_mask:0xf
	v_pk_fma_f32 v[16:17], v[44:45], v[16:17], v[56:57]
	v_pk_fma_f32 v[8:9], v[48:49], v[8:9], v[16:17]
	v_mov_b32_dpp v18, v90 row_ror:15 row_mask:0xf bank_mask:0xf
	v_mov_b32_dpp v19, v91 row_ror:15 row_mask:0xf bank_mask:0xf
	v_pk_fma_f32 v[8:9], v[52:53], v[18:19], v[8:9]
	global_store_dwordx4 v[42:43], v[26:29], off nt
	v_and_b32_e32 v19, 0x7fffffff, v9
	v_and_b32_e32 v18, 0x7fffffff, v8
	v_pk_fma_f32 v[18:19], v[18:19], s[56:57], 1.0 op_sel_hi:[1,0,0]
	v_pk_mul_f32 v[26:27], v[8:9], v[8:9]
	v_rcp_f32_e32 v18, v18
	v_rcp_f32_e32 v19, v19
	v_pk_mul_f32 v[26:27], v[26:27], s[54:55] op_sel_hi:[1,0]
	v_pk_fma_f32 v[22:23], v[18:19], s[58:59], v[24:25] op_sel_hi:[1,0,0]
	v_mov_b32_dpp v16, v96 row_ror:1 row_mask:0xf bank_mask:0xf
	v_pk_fma_f32 v[22:23], v[18:19], v[22:23], s[66:67] op_sel_hi:[1,1,0]
	v_mov_b32_dpp v17, v97 row_ror:1 row_mask:0xf bank_mask:0xf
	v_pk_fma_f32 v[22:23], v[18:19], v[22:23], s[68:69] op_sel_hi:[1,1,0]
	v_exp_f32_e32 v26, v26
	v_pk_fma_f32 v[22:23], v[18:19], v[22:23], s[72:73] op_sel_hi:[1,1,0]
	v_exp_f32_e32 v27, v27
	v_pk_fma_f32 v[16:17], v[46:47], v[16:17], v[58:59]
	v_pk_mul_f32 v[18:19], v[18:19], v[22:23]
	v_pk_fma_f32 v[16:17], v[50:51], v[10:11], v[16:17]
	v_mov_b32_dpp v22, v98 row_ror:15 row_mask:0xf bank_mask:0xf
	v_mov_b32_dpp v23, v99 row_ror:15 row_mask:0xf bank_mask:0xf
	v_pk_fma_f32 v[16:17], v[54:55], v[22:23], v[16:17]
	v_pk_mul_f32 v[18:19], v[26:27], v[18:19]
	v_and_b32_e32 v27, 0x7fffffff, v17
	v_and_b32_e32 v26, 0x7fffffff, v16
	v_pk_fma_f32 v[26:27], v[26:27], s[56:57], 1.0 op_sel_hi:[1,0,0]
	v_pk_mul_f32 v[22:23], v[8:9], v[18:19]
	v_rcp_f32_e32 v26, v26
	v_rcp_f32_e32 v27, v27
	v_pk_fma_f32 v[18:19], v[8:9], v[18:19], v[8:9] neg_lo:[1,0,0] neg_hi:[1,0,0]
	v_cmp_gt_f32_e32 vcc, 0, v9
	v_cndmask_b32_e64 v11, v15, v11, s[38:39]
	s_nop 0
	v_cndmask_b32_e32 v9, v19, v23, vcc
	v_cmp_gt_f32_e32 vcc, 0, v8
	s_nop 1
	v_cndmask_b32_e32 v8, v18, v22, vcc
	v_pk_mul_f32 v[22:23], v[16:17], v[16:17]
	v_pk_fma_f32 v[18:19], v[26:27], s[58:59], v[24:25] op_sel_hi:[1,0,0]
	v_pk_mul_f32 v[22:23], v[22:23], s[54:55] op_sel_hi:[1,0]
	v_pk_fma_f32 v[18:19], v[26:27], v[18:19], s[66:67] op_sel_hi:[1,1,0]
	v_exp_f32_e32 v22, v22
	v_exp_f32_e32 v23, v23
	v_pk_fma_f32 v[18:19], v[26:27], v[18:19], s[68:69] op_sel_hi:[1,1,0]
	v_cmp_gt_f32_e32 vcc, 0, v17
	v_pk_fma_f32 v[18:19], v[26:27], v[18:19], s[72:73] op_sel_hi:[1,1,0]
	v_pk_mul_f32 v[4:5], v[4:5], v[8:9]
	v_pk_mul_f32 v[18:19], v[26:27], v[18:19]
	v_cndmask_b32_e64 v9, v14, v10, s[38:39]
	v_pk_mul_f32 v[18:19], v[22:23], v[18:19]
	v_pk_mul_f32 v[22:23], v[16:17], v[18:19]
	v_pk_fma_f32 v[18:19], v[16:17], v[18:19], v[16:17] neg_lo:[1,0,0] neg_hi:[1,0,0]
	v_mov_b32_dpp v8, v9 row_ror:1 row_mask:0xf bank_mask:0xf
	v_cndmask_b32_e32 v17, v19, v23, vcc
	v_cmp_gt_f32_e32 vcc, 0, v16
	v_cndmask_b32_e64 v9, v14, 0, s[42:43]
	v_mov_b32_e32 v10, 0
	v_cndmask_b32_e32 v16, v18, v22, vcc
	v_pk_mul_f32 v[6:7], v[6:7], v[16:17]
	v_cvt_pk_bf16_f32 v22, v4, v5
	v_cvt_pk_bf16_f32 v23, v6, v7
	global_store_dwordx4 v[92:93], v[20:23], off nt
	v_mov_b32_dpp v10, v9 row_ror:15 row_mask:0xf bank_mask:0xf
	v_mov_b32_dpp v9, v11 row_ror:1 row_mask:0xf bank_mask:0xf
	v_cndmask_b32_e64 v16, v15, 0, s[42:43]
	v_mov_b32_dpp v4, v100 row_ror:1 row_mask:0xf bank_mask:0xf
	v_mov_b32_dpp v6, v94 row_ror:15 row_mask:0xf bank_mask:0xf
	v_mov_b32_dpp v5, v101 row_ror:1 row_mask:0xf bank_mask:0xf
	v_mov_b32_dpp v7, v95 row_ror:15 row_mask:0xf bank_mask:0xf
	v_mov_b32_dpp v11, v16 row_ror:15 row_mask:0xf bank_mask:0xf
	s_and_saveexec_b64 s[0:1], s[36:37]
	s_cbranch_execnz .LBB0_741
	s_or_b64 exec, exec, s[0:1]
	s_and_saveexec_b64 s[0:1], s[74:75]
	s_cbranch_execnz .LBB0_742
